# isel item start: removed the s_waitcnt vmcnt(0) that waited for the previous item's mask store
# baseline (speedup 1.0000x reference)
.LBB0_330:
	s_and_b32 s2, s45, 0xff
	s_ashr_i32 s1, s45, 9
	s_and_b32 s0, s45, 0x100
	s_xor_b32 s3, s2, 0x1ff
	s_cmp_eq_u32 s0, 0
	v_mov_b32_e32 v13, v212
	s_cselect_b32 s2, s2, s3
	s_lshl_b32 s29, s2, 3
	v_readfirstlane_b32 s0, v13
	s_lshl_b32 s49, s1, 12
	s_lshr_b32 s34, s2, 2
	s_ashr_i32 s0, s0, 6
	s_cmp_gt_i32 s0, s34
	v_and_b32_e32 v221, 63, v13
	s_cbranch_scc1 .LBB0_335
	s_or_b32 s6, s29, s49
	s_lshl_b32 s2, s2, 11
	s_lshl_b32 s4, s6, 1
	s_and_b32 s35, s2, 0xf000
	s_or_b32 s2, s4, 1
	s_ashr_i32 s3, s2, 31
	s_lshl_b64 s[38:39], s[2:3], 10
	s_or_b32 s2, s4, 2
	s_ashr_i32 s3, s2, 31
	s_lshl_b64 s[40:41], s[2:3], 10
	s_or_b32 s2, s4, 3
	s_ashr_i32 s3, s2, 31
	s_lshl_b64 s[42:43], s[2:3], 10
	s_ashr_i32 s2, s6, 8
	s_mulk_i32 s2, 0x49
	s_ashr_i32 s3, s2, 31
	s_lshl_b64 s[30:31], s[2:3], 17
	s_or_b32 s2, s4, 4
	s_ashr_i32 s3, s2, 31
	s_lshl_b64 s[20:21], s[2:3], 10
	s_or_b32 s2, s4, 5
	s_ashr_i32 s3, s2, 31
	s_lshl_b64 s[22:23], s[2:3], 10
	s_or_b32 s2, s4, 6
	s_ashr_i32 s3, s2, 31
	s_lshl_b64 s[24:25], s[2:3], 10
	s_or_b32 s2, s4, 7
	s_ashr_i32 s3, s2, 31
	s_lshl_b64 s[26:27], s[2:3], 10
	s_or_b32 s2, s4, 8
	s_ashr_i32 s3, s2, 31
	s_lshl_b64 s[12:13], s[2:3], 10
	s_or_b32 s2, s4, 9
	s_ashr_i32 s3, s2, 31
	s_lshl_b64 s[14:15], s[2:3], 10
	s_or_b32 s2, s4, 10
	s_ashr_i32 s5, s4, 31
	s_ashr_i32 s3, s2, 31
	s_lshl_b64 s[36:37], s[4:5], 10
	s_lshl_b64 s[16:17], s[2:3], 10
	s_or_b32 s2, s4, 11
	s_ashr_i32 s3, s2, 31
	s_lshl_b64 s[18:19], s[2:3], 10
	s_or_b32 s2, s4, 12
	s_or_b32 s6, s4, 13
	s_or_b32 s8, s4, 14
	s_or_b32 s4, s4, 15
	s_ashr_i32 s5, s4, 31
	s_lshl_b64 s[10:11], s[4:5], 10
	s_lshl_b32 s4, s1, 7
	s_ashr_i32 s3, s2, 31
	s_ashr_i32 s7, s6, 31
	s_ashr_i32 s9, s8, 31
	s_ashr_i32 s5, s4, 31
	s_lshl_b64 s[2:3], s[2:3], 10
	s_lshl_b64 s[6:7], s[6:7], 10
	s_lshl_b64 s[8:9], s[8:9], 10
	s_lshl_b64 s[4:5], s[4:5], 12
	v_readlane_b32 s36, v237, 5
	v_readlane_b32 s37, v237, 6
	s_add_u32 s30, s36, s30
	s_addc_u32 s31, s37, s31
	s_mov_b32 s1, 0x1bb00000
	s_mov_b64 s[30:31], 0x1bb00800
	s_mov_b32 s30, 0x3d000000
	v_readlane_b32 s36, v237, 46
	s_movk_i32 s41, 0x3fff
	s_mov_b32 s40, 0x800000
	s_movk_i32 s39, 0x1e0
	v_readlane_b32 s38, v237, 45
	v_readlane_b32 s37, v237, 47
	s_mov_b64 s[20:21], 0x1bb00880
	s_mov_b64 s[12:13], 0x1bb00900
	s_mov_b64 s[2:3], 0x1bb00980
	v_readlane_b32 s2, v239, 12
	v_readlane_b32 s3, v239, 13
	s_add_u32 s2, s2, s4
	s_addc_u32 s3, s3, s5
	s_ashr_i32 s1, s0, 31
	s_lshl_b64 s[2:3], s[0:1], 12
	s_lshl_b32 s1, s0, 7
	s_add_i32 s1, 0, 0x10000
	s_add_u32 s1, s2, s4
	s_addc_u32 s3, s3, s5
	v_readlane_b32 s2, v237, 3
	s_add_u32 s2, s2, s1
	v_readlane_b32 s1, v237, 4
	s_addc_u32 s3, s1, s3
	s_mov_b32 s1, s0
	v_lshlrev_b32_e32 v0, 4, v221
	v_lshrrev_b32_e32 v12, 5, v221
	v_and_b32_e32 v4, 31, v13
	s_or_b32 s2, s29, s49
	v_readlane_b32 s4, v237, 5
	v_readlane_b32 s5, v237, 6
	s_lshr_b32 s3, s2, 8
	s_mulk_i32 s3, 0x49
	s_lshl_b32 s3, s3, 17
	s_add_u32 s3, s3, 0x1bb00000
	s_add_u32 s4, s4, s3
	s_addc_u32 s5, s5, 0
	s_lshl_b32 s3, s29, 8
	s_and_b32 s3, s3, 0xf000
	v_or_b32_e32 v222, s29, v12
	v_lshlrev_b32_e32 v2, 5, v222
	v_and_b32_e32 v2, 0x120, v2
	v_or_b32_e32 v2, s3, v2
	v_lshlrev_b32_e32 v2, 1, v2
	v_mov_b32_e32 v3, v1
	v_lshl_add_u64 v[6:7], s[4:5], 0, v[2:3]
	global_load_dwordx4 v[18:21], v[6:7], off offset:2048
	global_load_dwordx4 v[22:25], v[6:7], off offset:2064
	global_load_dwordx4 v[26:29], v[6:7], off offset:2176
	global_load_dwordx4 v[30:33], v[6:7], off offset:2192
	global_load_dwordx4 v[34:37], v[6:7], off offset:2304
	global_load_dwordx4 v[38:41], v[6:7], off offset:2320
	global_load_dwordx4 v[42:45], v[6:7], off offset:2432
	global_load_dwordx4 v[46:49], v[6:7], off offset:2448
	s_lshl_b32 s3, s2, 11
	s_add_u32 s4, s82, s3
	s_addc_u32 s5, s83, 0
	s_add_u32 s4, s4, 0x1000
	s_addc_u32 s5, s5, 0
	v_lshl_add_u64 v[8:9], s[4:5], 0, v[0:1]
	s_add_u32 s4, s4, 0x2000
	s_addc_u32 s5, s5, 0
	v_lshl_add_u64 v[10:11], s[4:5], 0, v[0:1]
	global_load_dwordx4 v[66:69], v[8:9], off offset:-4096
	global_load_dwordx4 v[70:73], v[8:9], off offset:-3072
	global_load_dwordx4 v[74:77], v[8:9], off offset:-2048
	global_load_dwordx4 v[78:81], v[8:9], off offset:-1024
	global_load_dwordx4 v[82:85], v[8:9], off
	global_load_dwordx4 v[86:89], v[8:9], off offset:1024
	global_load_dwordx4 v[90:93], v[8:9], off offset:2048
	global_load_dwordx4 v[94:97], v[8:9], off offset:3072
	global_load_dwordx4 v[98:101], v[10:11], off offset:-4096
	global_load_dwordx4 v[102:105], v[10:11], off offset:-3072
	global_load_dwordx4 v[106:109], v[10:11], off offset:-2048
	global_load_dwordx4 v[110:113], v[10:11], off offset:-1024
	global_load_dwordx4 v[114:117], v[10:11], off
	global_load_dwordx4 v[118:121], v[10:11], off offset:1024
	global_load_dwordx4 v[122:125], v[10:11], off offset:2048
	global_load_dwordx4 v[126:129], v[10:11], off offset:3072
	v_readlane_b32 s4, v239, 12
	v_readlane_b32 s5, v239, 13
	s_lshl_b32 s3, s49, 7
	s_lshl_b32 s2, s0, 12
	s_add_u32 s3, s3, s2
	s_add_u32 s4, s4, s3
	s_addc_u32 s5, s5, 0
	v_lshl_add_u64 v[2:3], s[4:5], 0, v[0:1]
	global_load_dwordx4 v[130:133], v[2:3], off
	global_load_dwordx4 v[134:137], v[2:3], off offset:1024
	global_load_dwordx4 v[138:141], v[2:3], off offset:2048
	global_load_dwordx4 v[142:145], v[2:3], off offset:3072
	s_add_u32 s4, s4, 0x8800
	s_addc_u32 s5, s5, 0
	v_lshl_add_u64 v[210:211], s[4:5], 0, v[0:1]
	v_or_b32_e32 v223, 2, v222
	v_or_b32_e32 v224, 4, v222
	v_or_b32_e32 v225, 6, v222
	s_lshl_b32 s2, s0, 7
	v_lshlrev_b32_e32 v2, 14, v12
	v_lshl_or_b32 v2, v4, 2, v2
	v_add_u32_e32 v2, s2, v2
	v_add_u32_e32 v227, 0x10000, v2
	v_lshl_or_b32 v226, s0, 5, v4
	s_waitcnt vmcnt(20)
	v_and_b32_e32 v3, 0xffff0000, v18
	v_lshlrev_b32_e32 v2, 16, v18
	v_mul_f32_e32 v147, s30, v3
	v_mul_f32_e32 v146, s30, v2
	v_and_b32_e32 v3, 0xffff0000, v19
	v_lshlrev_b32_e32 v2, 16, v19
	v_mul_f32_e32 v149, s30, v3
	v_mul_f32_e32 v148, s30, v2
	v_and_b32_e32 v3, 0xffff0000, v20
	v_lshlrev_b32_e32 v2, 16, v20
	v_mul_f32_e32 v151, s30, v3
	v_mul_f32_e32 v150, s30, v2
	v_and_b32_e32 v3, 0xffff0000, v21
	v_lshlrev_b32_e32 v2, 16, v21
	v_mul_f32_e32 v153, s30, v3
	v_mul_f32_e32 v152, s30, v2
	v_and_b32_e32 v3, 0xffff0000, v22
	v_lshlrev_b32_e32 v2, 16, v22
	v_mul_f32_e32 v155, s30, v3
	v_mul_f32_e32 v154, s30, v2
	v_and_b32_e32 v3, 0xffff0000, v23
	v_lshlrev_b32_e32 v2, 16, v23
	v_mul_f32_e32 v157, s30, v3
	v_mul_f32_e32 v156, s30, v2
	v_and_b32_e32 v3, 0xffff0000, v24
	v_lshlrev_b32_e32 v2, 16, v24
	v_mul_f32_e32 v159, s30, v3
	v_mul_f32_e32 v158, s30, v2
	v_and_b32_e32 v3, 0xffff0000, v25
	v_lshlrev_b32_e32 v2, 16, v25
	v_mul_f32_e32 v161, s30, v3
	v_mul_f32_e32 v160, s30, v2
	v_and_b32_e32 v3, 0xffff0000, v26
	v_lshlrev_b32_e32 v2, 16, v26
	v_mul_f32_e32 v163, s30, v3
	v_mul_f32_e32 v162, s30, v2
	v_and_b32_e32 v3, 0xffff0000, v27
	v_lshlrev_b32_e32 v2, 16, v27
	v_mul_f32_e32 v165, s30, v3
	v_mul_f32_e32 v164, s30, v2
	v_and_b32_e32 v3, 0xffff0000, v28
	v_lshlrev_b32_e32 v2, 16, v28
	v_mul_f32_e32 v167, s30, v3
	v_mul_f32_e32 v166, s30, v2
	v_and_b32_e32 v3, 0xffff0000, v29
	v_lshlrev_b32_e32 v2, 16, v29
	v_mul_f32_e32 v169, s30, v3
	v_mul_f32_e32 v168, s30, v2
	v_and_b32_e32 v3, 0xffff0000, v30
	v_lshlrev_b32_e32 v2, 16, v30
	v_mul_f32_e32 v171, s30, v3
	v_mul_f32_e32 v170, s30, v2
	v_and_b32_e32 v3, 0xffff0000, v31
	v_lshlrev_b32_e32 v2, 16, v31
	v_mul_f32_e32 v173, s30, v3
	v_mul_f32_e32 v172, s30, v2
	v_and_b32_e32 v3, 0xffff0000, v32
	v_lshlrev_b32_e32 v2, 16, v32
	v_mul_f32_e32 v175, s30, v3
	v_mul_f32_e32 v174, s30, v2
	v_and_b32_e32 v3, 0xffff0000, v33
	v_lshlrev_b32_e32 v2, 16, v33
	v_mul_f32_e32 v177, s30, v3
	v_mul_f32_e32 v176, s30, v2
	v_and_b32_e32 v3, 0xffff0000, v34
	v_lshlrev_b32_e32 v2, 16, v34
	v_mul_f32_e32 v179, s30, v3
	v_mul_f32_e32 v178, s30, v2
	v_and_b32_e32 v3, 0xffff0000, v35
	v_lshlrev_b32_e32 v2, 16, v35
	v_mul_f32_e32 v181, s30, v3
	v_mul_f32_e32 v180, s30, v2
	v_and_b32_e32 v3, 0xffff0000, v36
	v_lshlrev_b32_e32 v2, 16, v36
	v_mul_f32_e32 v183, s30, v3
	v_mul_f32_e32 v182, s30, v2
	v_and_b32_e32 v3, 0xffff0000, v37
	v_lshlrev_b32_e32 v2, 16, v37
	v_mul_f32_e32 v185, s30, v3
	v_mul_f32_e32 v184, s30, v2
	v_and_b32_e32 v3, 0xffff0000, v38
	v_lshlrev_b32_e32 v2, 16, v38
	v_mul_f32_e32 v187, s30, v3
	v_mul_f32_e32 v186, s30, v2
	v_and_b32_e32 v3, 0xffff0000, v39
	v_lshlrev_b32_e32 v2, 16, v39
	v_mul_f32_e32 v189, s30, v3
	v_mul_f32_e32 v188, s30, v2
	v_and_b32_e32 v3, 0xffff0000, v40
	v_lshlrev_b32_e32 v2, 16, v40
	v_mul_f32_e32 v191, s30, v3
	v_mul_f32_e32 v190, s30, v2
	v_and_b32_e32 v3, 0xffff0000, v41
	v_lshlrev_b32_e32 v2, 16, v41
	v_mul_f32_e32 v193, s30, v3
	v_mul_f32_e32 v192, s30, v2
	v_and_b32_e32 v3, 0xffff0000, v42
	v_lshlrev_b32_e32 v2, 16, v42
	v_mul_f32_e32 v195, s30, v3
	v_mul_f32_e32 v194, s30, v2
	v_and_b32_e32 v3, 0xffff0000, v43
	v_lshlrev_b32_e32 v2, 16, v43
	v_mul_f32_e32 v197, s30, v3
	v_mul_f32_e32 v196, s30, v2
	v_and_b32_e32 v3, 0xffff0000, v44
	v_lshlrev_b32_e32 v2, 16, v44
	v_mul_f32_e32 v199, s30, v3
	v_mul_f32_e32 v198, s30, v2
	v_and_b32_e32 v3, 0xffff0000, v45
	v_lshlrev_b32_e32 v2, 16, v45
	v_mul_f32_e32 v201, s30, v3
	v_mul_f32_e32 v200, s30, v2
	v_and_b32_e32 v3, 0xffff0000, v46
	v_lshlrev_b32_e32 v2, 16, v46
	v_mul_f32_e32 v203, s30, v3
	v_mul_f32_e32 v202, s30, v2
	v_and_b32_e32 v3, 0xffff0000, v47
	v_lshlrev_b32_e32 v2, 16, v47
	v_mul_f32_e32 v205, s30, v3
	v_mul_f32_e32 v204, s30, v2
	v_and_b32_e32 v3, 0xffff0000, v48
	v_lshlrev_b32_e32 v2, 16, v48
	v_mul_f32_e32 v207, s30, v3
	v_mul_f32_e32 v206, s30, v2
	v_and_b32_e32 v3, 0xffff0000, v49
	v_lshlrev_b32_e32 v2, 16, v49
	v_mul_f32_e32 v209, s30, v3
	v_mul_f32_e32 v208, s30, v2
	s_branch .LBB0_333
